# priority 1 for workgroups while they run the E2 neighbourhood-attention jobs (reset at the job join), on top of the GEMM static raise
# speedup vs baseline: 1.0116x; 1.0116x over previous
.LBB0_442:
	s_add_i32 s0, s76, s77
	s_mul_hi_u32 s1, s0, s82
	s_mul_i32 s1, s1, s73
	s_sub_i32 s0, s0, s1
	s_sub_i32 s1, s0, s73
	s_cmp_ge_u32 s0, s73
	s_cselect_b32 s0, s1, s0
	s_sub_i32 s1, s0, s73
	s_cmp_ge_u32 s0, s73
	s_cselect_b32 s0, s1, s0
	s_mul_i32 s0, s0, s96
	v_readlane_b32 s1, v254, 46
	s_add_i32 s84, s0, s1
	s_cmpk_gt_i32 s84, 0x3ff
	s_mov_b64 s[0:1], -1
	s_cbranch_scc0 .LBB0_490
	s_cmpk_gt_u32 s84, 0x7ff
	s_cbranch_scc0 .LBB0_451
	s_setprio 1
	s_lshl_b32 s0, s84, 3
	s_and_b32 s0, s0, 0xffffff00
	s_lshl_b32 s1, s84, 6
	s_addk_i32 s0, 0xc000
	s_and_b32 s1, s1, 0xc0
	s_or_b32 s50, s0, s1
	s_mul_i32 s2, s50, 0x1a00
	s_mul_hi_u32 s1, s50, 0x1a00
	s_add_u32 s2, s44, s2
	s_addc_u32 s1, s45, s1
	s_lshl_b32 s3, s84, 4
	s_and_b32 s3, s3, 0x1c0
	v_mov_b32_e32 v25, v228
	s_lshl_b32 s4, s3, 1
	s_add_u32 s8, s2, s4
	v_ashrrev_i32_e32 v8, 31, v25
	v_lshrrev_b32_e32 v8, 29, v8
	s_addc_u32 s9, s1, 0
	s_mul_hi_u32 s1, s0, 0x1a00
	s_mulk_i32 s0, 0x1a00
	v_add_u32_e32 v10, v25, v8
	s_add_u32 s0, s44, s0
	v_ashrrev_i32_e32 v26, 3, v10
	v_and_b32_e32 v10, -8, v10
	s_addc_u32 s1, s45, s1
	v_ashrrev_i32_e32 v0, 2, v25
	s_movk_i32 s7, 0xd00
	v_sub_u32_e32 v27, v25, v10
	v_add_u32_e32 v14, 0x100, v25
	s_add_u32 s0, s0, s4
	v_bfi_b32 v44, -16, v0, v25
	v_mov_b64_e32 v[0:1], s[8:9]
	v_mad_i64_i32 v[8:9], s[8:9], v26, s7, 0
	v_lshlrev_b32_e32 v10, 3, v27
	v_ashrrev_i32_e32 v12, 31, v14
	s_addc_u32 s1, s1, 0
	v_bfe_u32 v2, v25, 4, 2
	v_lshlrev_b64 v[48:49], 1, v[8:9]
	v_ashrrev_i32_e32 v11, 31, v10
	v_lshrrev_b32_e32 v12, 29, v12
	v_mad_i64_i32 v[0:1], s[8:9], v44, s70, v[0:1]
	v_lshlrev_b32_e32 v196, 4, v2
	v_lshl_add_u64 v[8:9], s[0:1], 0, v[48:49]
	v_lshlrev_b64 v[50:51], 1, v[10:11]
	v_add_u32_e32 v15, v14, v12
	v_lshl_add_u64 v[0:1], v[0:1], 0, v[196:197]
	v_lshl_add_u64 v[16:17], v[8:9], 0, v[50:51]
	v_ashrrev_i32_e32 v28, 3, v15
	v_and_b32_e32 v15, -8, v15
	v_lshlrev_b32_e32 v46, 3, v2
	global_load_dwordx4 v[4:7], v[0:1], off
	s_nop 0
	global_load_dwordx4 v[0:3], v[0:1], off offset:64
	v_sub_u32_e32 v29, v14, v15
	global_load_dwordx4 v[8:11], v[16:17], off offset:1024
	v_mad_i64_i32 v[12:13], s[8:9], v28, s7, 0
	v_lshlrev_b32_e32 v14, 3, v29
	v_lshlrev_b64 v[52:53], 1, v[12:13]
	v_ashrrev_i32_e32 v15, 31, v14
	v_lshl_add_u64 v[12:13], s[0:1], 0, v[52:53]
	v_lshlrev_b64 v[54:55], 1, v[14:15]
	v_lshl_add_u64 v[20:21], v[12:13], 0, v[54:55]
	global_load_dwordx4 v[12:15], v[20:21], off offset:1024
	s_nop 0
	global_load_dwordx4 v[16:19], v[16:17], off offset:2048
	s_nop 0
	global_load_dwordx4 v[20:23], v[20:21], off offset:2048
	s_add_u32 s5, s0, 0x400
	v_and_b32_e32 v61, 15, v25
	s_movk_i32 s7, 0xa0
	v_bfe_u32 v30, v25, 2, 2
	v_lshlrev_b32_e32 v25, 3, v25
	s_addc_u32 s6, s1, 0
	v_and_b32_e32 v60, 24, v25
	v_mul_lo_u32 v25, v26, s7
	v_lshlrev_b32_e32 v27, 4, v27
	s_add_u32 s2, s0, 0x800
	v_add_u32_e32 v45, v25, v27
	s_addc_u32 s3, s1, 0
	s_waitcnt vmcnt(63) expcnt(7) lgkmcnt(15)
	s_barrier
	s_add_u32 s8, s0, 0x68400
	s_addc_u32 s9, s1, 0
	s_add_u32 s10, s0, 0x68800
	s_addc_u32 s11, s1, 0
	v_mul_lo_u32 v62, v44, s7
	v_or_b32_e32 v24, v62, v46
	v_add_u32_e32 v47, v62, v196
	v_or_b32_e32 v63, v46, v30
	s_waitcnt vmcnt(3)
	ds_write_b128 v45, v[8:11]
	v_lshlrev_b32_e32 v10, 4, v26
	v_sub_u32_e32 v10, v25, v10
	v_mul_lo_u32 v8, v28, s7
	v_lshlrev_b32_e32 v9, 4, v29
	v_add_u32_e32 v57, v10, v27
	v_lshlrev_b32_e32 v10, 4, v28
	v_add_u32_e32 v56, v8, v9
	v_sub_u32_e32 v8, v8, v10
	v_add_u32_e32 v58, v8, v9
	s_waitcnt vmcnt(2)
	ds_write_b128 v56, v[12:15]
	s_waitcnt vmcnt(1)
	ds_write_b128 v57, v[16:19] offset:10240
	s_waitcnt vmcnt(0)
	ds_write_b128 v58, v[20:23] offset:10240
	v_lshl_add_u64 v[8:9], s[8:9], 0, v[48:49]
	v_lshl_add_u64 v[12:13], s[8:9], 0, v[52:53]
	v_lshl_add_u64 v[16:17], s[10:11], 0, v[48:49]
	v_lshl_add_u64 v[20:21], s[10:11], 0, v[52:53]
	v_lshl_add_u64 v[8:9], v[8:9], 0, v[50:51]
	v_lshl_add_u64 v[12:13], v[12:13], 0, v[54:55]
	v_lshl_add_u64 v[16:17], v[16:17], 0, v[50:51]
	v_lshl_add_u64 v[20:21], v[20:21], 0, v[54:55]
	s_waitcnt lgkmcnt(0)
	s_barrier
	global_load_dwordx4 v[8:11], v[8:9], off
	s_nop 0
	global_load_dwordx4 v[12:15], v[12:13], off
	s_nop 0
	global_load_dwordx4 v[16:19], v[16:17], off
	s_nop 0
	global_load_dwordx4 v[20:23], v[20:21], off
	v_mad_u32_u24 v64, v61, s7, v196
	ds_read_b128 v[26:29], v64
	ds_read_b128 v[30:33], v64 offset:64
	s_mov_b32 s7, 0x3e38aa3b
	s_waitcnt lgkmcnt(1)
	v_mfma_f32_16x16x32_bf16 v[26:29], v[26:29], v[4:7], 0
	ds_read_b128 v[34:37], v64 offset:2624
	ds_read_b128 v[38:41], v64 offset:5184
	ds_read_b128 v[66:69], v64 offset:7744
	s_waitcnt lgkmcnt(3)
	v_mfma_f32_16x16x32_bf16 v[26:29], v[30:33], v[0:3], v[26:29]
	ds_read_b128 v[30:33], v64 offset:2560
	s_waitcnt lgkmcnt(0)
	v_mfma_f32_16x16x32_bf16 v[30:33], v[30:33], v[4:7], 0
	s_nop 4
	v_mul_f32_e32 v25, 0x3e38aa3b, v26
	v_mfma_f32_16x16x32_bf16 v[30:33], v[34:37], v[0:3], v[30:33]
	ds_read_b128 v[34:37], v64 offset:5120
	s_waitcnt lgkmcnt(0)
	v_mfma_f32_16x16x32_bf16 v[34:37], v[34:37], v[4:7], 0
	v_mfma_f32_16x16x32_bf16 v[34:37], v[38:41], v[0:3], v[34:37]
	ds_read_b128 v[38:41], v64 offset:7680
	s_waitcnt lgkmcnt(0)
	v_mfma_f32_16x16x32_bf16 v[38:41], v[38:41], v[4:7], 0
	v_mfma_f32_16x16x32_bf16 v[66:69], v[66:69], v[0:3], v[38:41]
	s_nop 6
	v_mul_f32_e32 v38, 0x3e38aa3b, v27
	v_max3_f32 v25, v25, s30, v38
	v_mul_f32_e32 v38, 0x3e38aa3b, v28
	v_mul_f32_e32 v39, 0x3e38aa3b, v29
	v_max3_f32 v25, v25, v38, v39
	v_mul_f32_e32 v38, 0x3e38aa3b, v30
	v_mul_f32_e32 v39, 0x3e38aa3b, v31
	v_max3_f32 v25, v25, v38, v39
	v_mul_f32_e32 v38, 0x3e38aa3b, v32
	v_mul_f32_e32 v39, 0x3e38aa3b, v33
	v_max3_f32 v25, v25, v38, v39
	v_mul_f32_e32 v38, 0x3e38aa3b, v34
	v_mul_f32_e32 v39, 0x3e38aa3b, v35
	v_max3_f32 v25, v25, v38, v39
	v_mul_f32_e32 v38, 0x3e38aa3b, v36
	v_mul_f32_e32 v39, 0x3e38aa3b, v37
	v_max3_f32 v25, v25, v38, v39
	v_mul_f32_e32 v38, 0x3e38aa3b, v66
	v_mul_f32_e32 v39, 0x3e38aa3b, v67
	v_max3_f32 v25, v25, v38, v39
	v_mul_f32_e32 v38, 0x3e38aa3b, v68
	v_mul_f32_e32 v39, 0x3e38aa3b, v69
	v_max3_f32 v25, v25, v38, v39
	v_mov_b32_e32 v38, v25
	s_nop 1
	v_permlane16_swap_b32_e32 v25, v38
	v_max_f32_e32 v38, v38, v38
	v_max_f32_e32 v25, v25, v25
	v_max_f32_e32 v25, v25, v38
	v_mov_b32_e32 v38, v25
	s_nop 1
	v_permlane32_swap_b32_e32 v25, v38
	v_max3_f32 v65, v25, v38, s30
	v_sub_f32_e32 v25, 0xf149f2ca, v65
	v_exp_f32_e32 v25, v25
	v_cmp_lt_f32_e32 vcc, s30, v65
	s_cmp_eq_u64 vcc, 0
	s_cselect_b64 vcc, -1, 0
	v_mul_f32_e32 v25, 0, v25
	v_cndmask_b32_e64 v40, v25, 0, vcc
	v_fma_f32 v25, v26, s7, -v65
	v_exp_f32_e32 v26, v25
	v_fma_f32 v25, v27, s7, -v65
	v_exp_f32_e32 v38, v25
	v_fma_f32 v25, v28, s7, -v65
	v_exp_f32_e32 v27, v25
	v_fma_f32 v25, v29, s7, -v65
	v_exp_f32_e32 v39, v25
	v_fma_f32 v25, v30, s7, -v65
	v_cndmask_b32_e32 v59, v65, v235, vcc
	v_mov_b32_e32 v41, v40
	v_pk_add_f32 v[28:29], v[26:27], v[38:39]
	v_cvt_pk_bf16_f32 v26, v26, v38
	v_add_f32_e32 v70, v28, v29
	v_exp_f32_e32 v28, v25
	v_fma_f32 v25, v31, s7, -v65
	v_exp_f32_e32 v30, v25
	v_fma_f32 v25, v32, s7, -v65
	v_exp_f32_e32 v29, v25
	v_fma_f32 v25, v33, s7, -v65
	v_exp_f32_e32 v31, v25
	v_cvt_pk_bf16_f32 v27, v27, v39
	v_add_u32_e32 v38, 0x4800, v24
	v_fma_f32 v24, v34, s7, -v65
	v_pk_add_f32 v[32:33], v[28:29], v[30:31]
	v_cvt_pk_bf16_f32 v28, v28, v30
	v_cvt_pk_bf16_f32 v29, v29, v31
	ds_write2_b64 v38, v[26:27], v[28:29] offset0:128 offset1:132
	v_fma_f32 v25, v35, s7, -v65
	v_fma_f32 v26, v36, s7, -v65
	v_fma_f32 v27, v37, s7, -v65
	v_exp_f32_e32 v24, v24
	v_exp_f32_e32 v25, v25
	v_exp_f32_e32 v26, v26
	v_exp_f32_e32 v27, v27
	v_pk_add_f32 v[32:33], v[32:33], v[32:33] op_sel_hi:[0,1]
	v_add_f32_e32 v29, v24, v25
	v_cvt_pk_bf16_f32 v24, v24, v25
	v_add_f32_e32 v31, v26, v27
	v_cvt_pk_bf16_f32 v25, v26, v27
	v_fma_f32 v26, v66, s7, -v65
	v_exp_f32_e32 v28, v26
	v_fma_f32 v26, v67, s7, -v65
	v_exp_f32_e32 v30, v26
	v_fma_f32 v26, v68, s7, -v65
	v_exp_f32_e32 v32, v26
	v_fma_f32 v26, v69, s7, -v65
	v_exp_f32_e32 v34, v26
	v_add_f32_e32 v35, 0, v70
	v_cvt_pk_bf16_f32 v26, v28, v30
	v_pk_add_f32 v[28:29], v[28:29], v[30:31]
	v_pk_add_f32 v[30:31], v[32:33], v[34:35]
	s_movk_i32 s7, 0x90
	v_cvt_pk_bf16_f32 v27, v32, v34
	v_pk_add_f32 v[28:29], v[28:29], v[30:31]
	v_mad_u32_u24 v74, v63, s7, v60
	ds_write2_b64 v38, v[24:25], v[26:27] offset0:136 offset1:140
	ds_read_b128 v[24:27], v47 offset:19456
	ds_read_b128 v[66:69], v47 offset:19520
	v_add_f32_e32 v65, v28, v29
	ds_read_b64_tr_b16 v[30:31], v74 offset:10816
	ds_read_b64_tr_b16 v[28:29], v74 offset:10240
	ds_read_b64_tr_b16 v[32:33], v74 offset:10272
	ds_read_b64_tr_b16 v[34:35], v74 offset:10848
	ds_read_b64_tr_b16 v[36:37], v74 offset:10304
	ds_read_b64_tr_b16 v[38:39], v74 offset:10880
	v_mov_b32_e32 v42, v40
	v_mov_b32_e32 v43, v40
	s_add_u32 s8, s0, 0xd0400
	s_addc_u32 s9, s1, 0
	s_waitcnt lgkmcnt(0)
	v_mfma_f32_16x16x32_bf16 v[70:73], v[36:39], v[24:27], v[40:43]
	ds_read_b64_tr_b16 v[36:37], v74 offset:10336
	ds_read_b64_tr_b16 v[38:39], v74 offset:10912
	s_add_u32 s0, s0, 0xd0800
	s_addc_u32 s1, s1, 0
	v_mfma_f32_16x16x32_bf16 v[28:31], v[28:31], v[24:27], v[40:43]
	v_mfma_f32_16x16x32_bf16 v[32:35], v[32:35], v[24:27], v[40:43]
	s_waitcnt lgkmcnt(0)
	v_mfma_f32_16x16x32_bf16 v[24:27], v[36:39], v[24:27], v[40:43]
	ds_read_b64_tr_b16 v[36:37], v74 offset:14848
	ds_read_b64_tr_b16 v[38:39], v74 offset:15424
	s_nop 0
	v_add_f32_e32 v42, v40, v65
	s_waitcnt lgkmcnt(0)
	v_mfma_f32_16x16x32_bf16 v[36:39], v[36:39], v[66:69], v[28:31]
	s_nop 2
	ds_read_b64_tr_b16 v[28:29], v74 offset:14880
	ds_read_b64_tr_b16 v[30:31], v74 offset:15456
	s_waitcnt lgkmcnt(0)
	v_mfma_f32_16x16x32_bf16 v[28:31], v[28:31], v[66:69], v[32:35]
	s_nop 2
	ds_read_b64_tr_b16 v[32:33], v74 offset:14912
	ds_read_b64_tr_b16 v[34:35], v74 offset:15488
	s_waitcnt lgkmcnt(0)
	v_mfma_f32_16x16x32_bf16 v[32:35], v[32:35], v[66:69], v[70:73]
	s_nop 2
	ds_read_b64_tr_b16 v[70:71], v74 offset:14944
	ds_read_b64_tr_b16 v[72:73], v74 offset:15520
	s_waitcnt lgkmcnt(0)
	s_barrier
	s_waitcnt vmcnt(3)
	ds_write_b128 v45, v[8:11]
	s_waitcnt vmcnt(2)
	ds_write_b128 v56, v[12:15]
	s_waitcnt vmcnt(1)
	ds_write_b128 v57, v[16:19] offset:10240
	s_waitcnt vmcnt(0)
	ds_write_b128 v58, v[20:23] offset:10240
	v_lshl_add_u64 v[8:9], s[8:9], 0, v[48:49]
	v_lshl_add_u64 v[12:13], s[8:9], 0, v[52:53]
	v_lshl_add_u64 v[16:17], s[0:1], 0, v[48:49]
	v_lshl_add_u64 v[20:21], s[0:1], 0, v[52:53]
	v_lshl_add_u64 v[8:9], v[8:9], 0, v[50:51]
	v_lshl_add_u64 v[12:13], v[12:13], 0, v[54:55]
	v_lshl_add_u64 v[16:17], v[16:17], 0, v[50:51]
	v_lshl_add_u64 v[20:21], v[20:21], 0, v[54:55]
	s_waitcnt lgkmcnt(0)
	s_barrier
	global_load_dwordx4 v[8:11], v[8:9], off
	v_mfma_f32_16x16x32_bf16 v[24:27], v[70:73], v[66:69], v[24:27]
	global_load_dwordx4 v[12:15], v[12:13], off
	s_nop 0
	global_load_dwordx4 v[16:19], v[16:17], off
	s_nop 0
	global_load_dwordx4 v[20:23], v[20:21], off
	ds_read_b128 v[66:69], v64
	ds_read_b128 v[70:73], v64 offset:64
	s_waitcnt lgkmcnt(1)
	v_mfma_f32_16x16x32_bf16 v[66:69], v[66:69], v[4:7], 0
	ds_read_b128 v[74:77], v64 offset:2624
	s_waitcnt lgkmcnt(1)
	v_mfma_f32_16x16x32_bf16 v[66:69], v[70:73], v[0:3], v[66:69]
	ds_read_b128 v[70:73], v64 offset:2560
	s_waitcnt lgkmcnt(0)
	v_mfma_f32_16x16x32_bf16 v[70:73], v[70:73], v[4:7], 0
	v_mfma_f32_16x16x32_bf16 v[78:81], v[74:77], v[0:3], v[70:73]
	ds_read_b128 v[74:77], v64 offset:5184
	s_nop 5
	ds_read_b128 v[70:73], v64 offset:5120
	s_waitcnt lgkmcnt(0)
	v_mfma_f32_16x16x32_bf16 v[70:73], v[70:73], v[4:7], 0
	v_mul_f32_e32 v41, 0x3e38aa3b, v78
	v_mfma_f32_16x16x32_bf16 v[82:85], v[74:77], v[0:3], v[70:73]
	ds_read_b128 v[74:77], v64 offset:7744
	s_nop 4
	ds_read_b128 v[70:73], v64 offset:7680
	s_waitcnt lgkmcnt(0)
	v_mfma_f32_16x16x32_bf16 v[70:73], v[70:73], v[4:7], 0
	v_mfma_f32_16x16x32_bf16 v[86:89], v[74:77], v[0:3], v[70:73]
	v_mul_f32_e32 v75, 0x3e38aa3b, v66
	v_mul_f32_e32 v74, 0x3e38aa3b, v67
	v_max3_f32 v40, v75, s30, v74
	v_mul_f32_e32 v77, 0x3e38aa3b, v68
	v_mul_f32_e32 v76, 0x3e38aa3b, v69
	v_max3_f32 v40, v40, v77, v76
	s_nop 0
	v_mul_f32_e32 v71, 0x3e38aa3b, v79
	v_max3_f32 v40, v40, v41, v71
	v_mul_f32_e32 v73, 0x3e38aa3b, v80
	v_mul_f32_e32 v72, 0x3e38aa3b, v81
	v_max3_f32 v40, v40, v73, v72
	v_mul_f32_e32 v68, 0x3e38aa3b, v82
	v_mul_f32_e32 v67, 0x3e38aa3b, v83
	v_max3_f32 v40, v40, v68, v67
	v_mul_f32_e32 v70, 0x3e38aa3b, v84
	v_mul_f32_e32 v69, 0x3e38aa3b, v85
	v_max3_f32 v40, v40, v70, v69
	v_mul_f32_e32 v65, 0x3e38aa3b, v86
	v_mul_f32_e32 v43, 0x3e38aa3b, v87
	v_max3_f32 v66, v40, v65, v43
	v_mul_f32_e32 v64, 0x3e38aa3b, v88
	v_mul_f32_e32 v40, 0x3e38aa3b, v89
	v_max3_f32 v66, v66, v64, v40
	v_mov_b32_e32 v78, v66
	s_nop 1
	v_permlane16_swap_b32_e32 v66, v78
	v_max_f32_e32 v78, v78, v78
	v_max_f32_e32 v66, v66, v66
	v_max_f32_e32 v66, v66, v78
	v_mov_b32_e32 v78, v66
	s_nop 1
	v_permlane32_swap_b32_e32 v66, v78
	v_max3_f32 v66, v59, v66, v78
	v_cmp_gt_f32_e32 vcc, v66, v59
	s_cbranch_vccz .LBB0_446
	v_sub_f32_e32 v59, v59, v66
	v_exp_f32_e32 v78, v59
	v_mov_b32_e32 v59, v66
	v_pk_mul_f32 v[38:39], v[38:39], v[78:79] op_sel_hi:[1,0]
	v_pk_mul_f32 v[36:37], v[36:37], v[78:79] op_sel_hi:[1,0]
	v_pk_mul_f32 v[30:31], v[30:31], v[78:79] op_sel_hi:[1,0]
	v_pk_mul_f32 v[28:29], v[28:29], v[78:79] op_sel_hi:[1,0]
	v_pk_mul_f32 v[34:35], v[34:35], v[78:79] op_sel_hi:[1,0]
	v_pk_mul_f32 v[32:33], v[32:33], v[78:79] op_sel_hi:[1,0]
	v_pk_mul_f32 v[26:27], v[26:27], v[78:79] op_sel_hi:[1,0]
	v_pk_mul_f32 v[24:25], v[24:25], v[78:79] op_sel_hi:[1,0]
	v_mul_f32_e32 v42, v42, v78

.LBB0_451:
	s_setprio 1
	s_and_b64 vcc, exec, s[0:1]
	s_cbranch_vccz .LBB0_494
	s_add_i32 s0, s84, 0xfffffc00
	s_lshr_b32 s2, s0, 9
	s_and_b32 s3, s84, 63
	s_lshl_b32 s0, s2, 12
	v_med3_u32 v80, s3, 4, 60
	s_addk_i32 s0, 0x2000
	s_lshl_b32 s1, s3, 6
	s_or_b32 s50, s0, s1
	v_readfirstlane_b32 s1, v80
	s_lshl_b32 s1, s1, 6
	s_or_b32 s0, s1, s0
	s_bfe_u32 s8, s84, 0x30006
	s_add_i32 s9, s0, 0xffffff00
	s_mul_i32 s1, s50, 0x1a00
	s_mul_hi_u32 s0, s50, 0x1a00
	s_add_u32 s1, s44, s1
	s_addc_u32 s4, s45, s0
	s_lshl_b32 s96, s8, 6
	s_lshl_b32 s10, s8, 7
	s_add_u32 s0, s1, s10
	v_mov_b32_e32 v10, v228
	s_addc_u32 s1, s4, 0
	s_lshl_b32 s2, s2, 1
	v_ashrrev_i32_e32 v0, 2, v10
	v_bfe_u32 v11, v10, 4, 2
	v_and_b32_e32 v13, -16, v0
	v_bfi_b32 v56, -16, v0, v10
	v_mov_b64_e32 v[0:1], s[0:1]
	v_mad_i64_i32 v[0:1], s[0:1], v56, s70, v[0:1]
	v_lshlrev_b32_e32 v196, 4, v11
	v_lshl_add_u64 v[0:1], v[0:1], 0, v[196:197]
	global_load_dwordx4 v[20:23], v[0:1], off
	global_load_dwordx4 v[16:19], v[0:1], off offset:64
	v_ashrrev_i32_e32 v0, 31, v10
	v_lshrrev_b32_e32 v0, 29, v0
	v_add_u32_e32 v4, v10, v0
	v_readlane_b32 s4, v254, 52
	v_ashrrev_i32_e32 v60, 3, v4
	v_and_b32_e32 v4, -8, v4
	s_add_i32 s4, s2, s4
	s_mov_b32 s5, s51
	v_sub_u32_e32 v40, v10, v4
	s_lshl_b64 s[4:5], s[4:5], 19
	v_readlane_b32 s6, v253, 5
	v_lshlrev_b32_e32 v4, 3, v40
	v_readlane_b32 s7, v253, 6
	s_add_u32 s56, s6, s4
	v_ashrrev_i32_e32 v5, 31, v4
	v_add_u32_e32 v8, 0x100, v10
	s_addc_u32 s57, s7, s5
	v_lshlrev_b64 v[62:63], 1, v[4:5]
	v_ashrrev_i32_e32 v4, 31, v8
	s_add_u32 s6, s56, s10
	v_lshrrev_b32_e32 v4, 29, v4
	s_addc_u32 s7, s57, 0
	v_readlane_b32 s12, v253, 3
	v_add_u32_e32 v9, v8, v4
	v_readlane_b32 s13, v253, 4
	s_add_u32 s64, s12, s4
	v_ashrrev_i32_e32 v64, 3, v9
	v_and_b32_e32 v9, -8, v9
	s_addc_u32 s65, s13, s5
	v_ashrrev_i32_e32 v61, 31, v60
	v_sub_u32_e32 v41, v8, v9
	s_add_u32 s4, s64, s10
	v_lshlrev_b64 v[0:1], 10, v[60:61]
	v_ashrrev_i32_e32 v65, 31, v64
	v_lshlrev_b32_e32 v8, 3, v41
	s_addc_u32 s5, s65, 0
	v_lshl_add_u64 v[2:3], s[6:7], 0, v[0:1]
	v_lshlrev_b64 v[4:5], 10, v[64:65]
	v_ashrrev_i32_e32 v9, 31, v8
	v_lshl_add_u64 v[2:3], v[2:3], 0, v[62:63]
	v_lshl_add_u64 v[6:7], s[6:7], 0, v[4:5]
	v_lshlrev_b64 v[66:67], 1, v[8:9]
	v_lshl_add_u64 v[0:1], s[4:5], 0, v[0:1]
	v_lshl_add_u64 v[6:7], v[6:7], 0, v[66:67]
	global_load_dwordx4 v[28:31], v[2:3], off
	global_load_dwordx4 v[24:27], v[6:7], off
	v_lshl_add_u64 v[0:1], v[0:1], 0, v[62:63]
	v_lshl_add_u64 v[2:3], s[4:5], 0, v[4:5]
	v_lshl_add_u64 v[2:3], v[2:3], 0, v[66:67]
	global_load_dwordx4 v[36:39], v[0:1], off
	global_load_dwordx4 v[32:35], v[2:3], off
	s_mul_hi_u32 s2, s9, 0x1a00
	s_mulk_i32 s9, 0x1a00
	s_add_u32 s9, s44, s9
	s_addc_u32 s2, s45, s2
	s_add_u32 s60, s9, 0x400
	s_addc_u32 s61, s2, 0
	s_add_u32 s62, s9, 0x800
	s_addc_u32 s63, s2, 0
	v_readlane_b32 s2, v254, 57
	s_or_b32 s2, s8, s2
	s_mul_i32 s8, s2, 0x1d1
	s_mov_b32 s9, s51
	v_med3_i32 v14, v56, 8, 56
	v_lshlrev_b32_e32 v58, 2, v11
	s_lshl_b64 s[8:9], s[8:9], 2
	v_readlane_b32 s12, v252, 29
	v_add_u32_e32 v15, -8, v14
	v_add_u32_e32 v0, 8, v14
	s_movk_i32 s0, 0xa0
	v_or_b32_e32 v79, 16, v58
	v_readlane_b32 s13, v252, 30
	v_readlane_b32 s24, v252, 41
	v_readlane_b32 s25, v252, 42
	s_add_u32 s54, s12, s8
	v_mul_lo_u32 v85, v56, s0
	v_mul_lo_u32 v86, v60, s0
	v_mul_lo_u32 v88, v64, s0
	v_cmp_ge_u32_e32 vcc, v79, v15
	v_cmp_lt_u32_e64 s[0:1], v79, v0
	v_or_b32_e32 v78, 17, v58
	v_readlane_b32 s22, v252, 39
	v_readlane_b32 s23, v252, 40
	s_addc_u32 s55, s13, s9
	v_add_u32_e32 v109, 0x100, v228
	v_min_u32_e32 v109, 0x1d0, v109
	v_lshlrev_b32_e32 v110, 2, v228
	v_lshlrev_b32_e32 v109, 2, v109
	global_load_dword v108, v110, s[54:55]
	global_load_dword v109, v109, s[54:55]
	s_and_b64 s[24:25], vcc, s[0:1]
	v_cmp_ge_u32_e32 vcc, v78, v15
	v_cmp_lt_u32_e64 s[0:1], v78, v0
	v_or_b32_e32 v77, 18, v58
	v_readlane_b32 s20, v252, 37
	v_readlane_b32 s21, v252, 38
	s_and_b64 s[22:23], vcc, s[0:1]
	v_cmp_ge_u32_e32 vcc, v77, v15
	v_cmp_lt_u32_e64 s[0:1], v77, v0
	v_or_b32_e32 v76, 19, v58
	v_readlane_b32 s18, v252, 35
	v_readlane_b32 s19, v252, 36
	s_and_b64 s[20:21], vcc, s[0:1]
	v_cmp_ge_u32_e32 vcc, v76, v15
	v_cmp_lt_u32_e64 s[0:1], v76, v0
	v_or_b32_e32 v75, 32, v58
	v_readlane_b32 s16, v252, 33
	v_readlane_b32 s17, v252, 34
	s_and_b64 s[18:19], vcc, s[0:1]
	v_cmp_ge_u32_e32 vcc, v75, v15
	v_cmp_lt_u32_e64 s[0:1], v75, v0
	v_or_b32_e32 v74, 33, v58
	v_readlane_b32 s14, v252, 31
	v_readlane_b32 s15, v252, 32
	s_and_b64 s[16:17], vcc, s[0:1]
	v_cmp_ge_u32_e32 vcc, v74, v15
	v_cmp_lt_u32_e64 s[0:1], v74, v0
	v_or_b32_e32 v73, 34, v58
	v_lshlrev_b32_e32 v84, 3, v11
	v_bfe_u32 v1, v10, 2, 2
	s_and_b64 s[14:15], vcc, s[0:1]
	v_cmp_ge_u32_e32 vcc, v73, v15
	v_cmp_lt_u32_e64 s[0:1], v73, v0
	v_or_b32_e32 v72, 35, v58
	v_or_b32_e32 v1, v84, v1
	s_and_b64 s[12:13], vcc, s[0:1]
	v_cmp_ge_u32_e32 vcc, v72, v15
	v_cmp_lt_u32_e64 s[0:1], v72, v0
	v_or_b32_e32 v71, 48, v58
	v_or_b32_e32 v70, 49, v58
	v_or_b32_e32 v69, 50, v58
	v_or_b32_e32 v68, 51, v58
	v_and_b32_e32 v12, 15, v10
	s_and_b64 s[10:11], vcc, s[0:1]
	v_cmp_lt_u32_e64 s[8:9], v71, v0
	v_cmp_lt_u32_e64 s[6:7], v70, v0
	v_cmp_lt_u32_e64 s[4:5], v69, v0
	v_cmp_lt_u32_e64 s[40:41], v68, v0
	v_mul_u32_u24_e32 v6, 0x90, v1
	v_mad_u64_u32 v[0:1], s[0:1], v80, 31, v[58:59]
	v_lshlrev_b32_e32 v2, 3, v10
	v_lshlrev_b32_e32 v3, 4, v60
	v_lshlrev_b32_e32 v4, 4, v64
	v_sub_u32_e32 v0, v0, v12
	v_readlane_b32 s26, v252, 43
	v_readlane_b32 s27, v252, 44
	v_and_b32_e32 v2, 24, v2
	v_lshlrev_b32_e32 v87, 4, v40
	v_lshlrev_b32_e32 v89, 4, v41
	v_sub_u32_e32 v3, v86, v3
	v_sub_u32_e32 v4, v88, v4
	v_mul_u32_u24_e32 v5, 0xa0, v12
	v_or_b32_e32 v83, 1, v58
	v_or_b32_e32 v82, 2, v58
	v_or_b32_e32 v81, 3, v58
	v_sub_u32_e32 v0, v0, v13
	s_mul_i32 s0, s3, 31
	v_mov_b32_e32 v8, v197
	v_mov_b32_e32 v9, v197
	v_mov_b32_e32 v10, v197
	v_mov_b32_e32 v11, v197
	v_cmp_lt_u32_e64 s[34:35], v58, v15
	v_cmp_lt_u32_e64 s[30:31], v83, v15
	v_cmp_lt_u32_e64 s[28:29], v82, v15
	v_cmp_lt_u32_e64 s[26:27], v81, v15
	v_subrev_u32_e32 v91, s0, v0
	v_add_u32_e32 v92, v3, v87
	v_add_u32_e32 v93, v4, v89
	v_add_u32_e32 v90, v196, v5
	v_add_u32_e32 v61, v2, v6
	v_mov_b64_e32 v[0:1], v[8:9]
	v_mov_b64_e32 v[4:5], v[8:9]
	v_mov_b64_e32 v[14:15], v[10:11]
	s_mov_b32 s72, 0xf149f2ca
	v_ashrrev_i32_e32 v57, 31, v56
	s_mov_b32 s97, 0
	v_mov_b32_e32 v59, 0
	v_mov_b32_e32 v65, 0xf149f2ca
	s_mov_b32 s42, -7
	v_mov_b64_e32 v[2:3], v[10:11]
	v_mov_b64_e32 v[6:7], v[10:11]
	v_mov_b64_e32 v[12:13], v[8:9]
	s_mov_b32 s43, 0
	s_branch .LBB0_454

.LBB0_490:
	s_setprio 0
	s_andn2_b64 vcc, exec, s[0:1]
	s_cbranch_vccnz .LBB0_441
	s_branch .LBB0_495

.LBB0_549:
	s_setprio 0
	s_getreg_b32 s2, hwreg(HW_REG_XCC_ID, 0, 4)
	s_waitcnt vmcnt(0)
	s_barrier
	s_and_saveexec_b64 s[0:1], s[24:25]
	s_cbranch_execz .LBB0_601
	s_waitcnt vmcnt(0) expcnt(0) lgkmcnt(0)
	ds_read_b32 v2, v197 offset:61440
	ds_read_b32 v0, v197 offset:61444
	s_and_b32 s2, s2, 15
	s_waitcnt lgkmcnt(1)
	v_cmp_ne_u32_e32 vcc, 0, v2
	s_cbranch_vccnz .LBB0_565
	s_mov_b32 s3, 1
	s_branch .LBB0_553
